# FoX softmax head: pad-row masking of the first key tile (24 v_cndmask) skipped by a scalar branch on all other tiles
# speedup vs baseline: 1.0109x; 1.0066x over previous
; template <int TYPE>
; __device__ __forceinline__ void attn_item(const Params& p, int layer, int head, int qb, int mode, LAS unsigned char* lds) {
;     ...
;             if (t == T0) {
;                 const int lo = (PADR & 63) - 4 * hi; const float NEGI = -__builtin_inff();
; #pragma unroll
;                 for (int r = 0; r < 16; ++r) { const int c = (r & 3) + 8 * (r >> 2); if (c < lo) p0[r] = NEGI; if (c + 32 < lo) p1[r] = NEGI; }
;             }
.LBB0_853:
	s_cmpk_eq_i32 s18, 0xc0
	s_cselect_b64 vcc, -1, 0
	s_cbranch_scc0 .Lfox_nomask
	v_cndmask_b32_e32 v82, v82, v219, vcc
	v_cndmask_b32_e32 v83, v83, v219, vcc
	v_cndmask_b32_e32 v74, v98, v219, vcc
	v_cndmask_b32_e32 v79, v97, v219, vcc
	v_cndmask_b32_e32 v85, v85, v219, vcc
	v_cndmask_b32_e32 v84, v84, v219, vcc
	v_cndmask_b32_e32 v87, v87, v219, vcc
	v_cndmask_b32_e32 v86, v86, v219, vcc
	v_cndmask_b32_e32 v89, v89, v219, vcc
	v_cndmask_b32_e32 v88, v88, v219, vcc
	v_cndmask_b32_e32 v91, v91, v219, vcc
	v_cndmask_b32_e32 v90, v90, v219, vcc
	v_cndmask_b32_e32 v93, v93, v219, vcc
	v_cndmask_b32_e32 v92, v92, v219, vcc
	v_cndmask_b32_e32 v95, v95, v219, vcc
	v_cndmask_b32_e32 v94, v94, v219, vcc
	v_cndmask_b32_e32 v96, v96, v219, vcc
	v_cndmask_b32_e32 v73, v73, v219, vcc
	v_cndmask_b32_e32 v72, v72, v219, vcc
	v_cndmask_b32_e32 v75, v101, v219, vcc
	v_cndmask_b32_e32 v78, v100, v219, vcc
	v_cndmask_b32_e32 v71, v71, v219, vcc
	v_cndmask_b32_e32 v70, v70, v219, vcc
	v_cndmask_b32_e32 v0, v99, v219, vcc
	s_branch .Lfox_maxchain
.Lfox_nomask:
	v_mov_b32_e32 v74, v98
	v_mov_b32_e32 v79, v97
	v_mov_b32_e32 v75, v101
	v_mov_b32_e32 v78, v100
	v_mov_b32_e32 v0, v99
; __device__ __forceinline__ int crow(int r, int hi) { return (r & 3) + 8 * (r >> 2) + 4 * hi; }
; template <int TYPE>
; __device__ __forceinline__ void attn_item(const Params& p, int layer, int head, int qb, int mode, LAS unsigned char* lds) {
;     ...
;             float pmax = p0[0];
; #pragma unroll
;             for (int r = 1; r < 16; ++r) pmax = fmaxf(pmax, p0[r]);
; #pragma unroll
;             for (int r = 0; r < 16; ++r) pmax = fmaxf(pmax, p1[r]);
;             { auto rr = __builtin_amdgcn_permlane32_swap(__float_as_uint(pmax), __float_as_uint(pmax), false, false);
;               pmax = fmaxf(__uint_as_float(rr[0]), __uint_as_float(rr[1])); }
;             float mn, alpha;
;             if (__all((pmax - m_reg) <= (TYPE == 1 ? 2.0f : 11.5f))) { mn = m_reg; alpha = 1.f; }
;             else { mn = fmaxf(m_reg, pmax); alpha = __builtin_amdgcn_exp2f(m_reg - mn); m_reg = mn; }
;             float ps = 0.f;
; #pragma unroll
;             for (int r = 0; r < 16; ++r) { p0[r] = __builtin_amdgcn_exp2f(p0[r] - mn); p1[r] = __builtin_amdgcn_exp2f(p1[r] - mn); ps += p0[r] + p1[r]; }
;             { auto rr = __builtin_amdgcn_permlane32_swap(__float_as_uint(ps), __float_as_uint(ps), false, false);
;               ps = __uint_as_float(rr[0]) + __uint_as_float(rr[1]); }
;             l_reg = l_reg * alpha + ps;
;             bf16x8 pa0, pa1, pa2, pa3;
;     ...
;             PK4(p0, 0, pa0); PK4(p0, 8, pa1); PK4(p1, 0, pa2); PK4(p1, 8, pa3);
;     ...
;             if (__any(alpha < 1.f)) {
;                 if (hi == 0) wsl[r32] = alpha;
;                 asm volatile("s_waitcnt lgkmcnt(0)" ::: "memory");
; #pragma unroll
;                 for (int r = 0; r < 16; ++r) { const float al = wsl[crow(r, hi)];
; #pragma unroll
;                     for (int d = 0; d < 4; ++d) o[d][r] *= al; }
;             }
.Lfox_maxchain:
	v_max_f32_e32 v97, v83, v83
	v_max_f32_e32 v98, v82, v82
	v_max_f32_e32 v97, v98, v97
	v_max3_f32 v97, v97, v84, v85
	v_max3_f32 v97, v97, v86, v87
	v_max3_f32 v97, v97, v88, v89
	v_max3_f32 v97, v97, v90, v91
	v_max3_f32 v97, v97, v92, v93
	v_max3_f32 v97, v97, v94, v95
	v_max3_f32 v97, v97, v96, v79
	v_max3_f32 v97, v97, v72, v73
	v_max3_f32 v97, v97, v78, v75
	v_max3_f32 v97, v97, v70, v71
	v_max3_f32 v97, v97, v74, v0
	v_max3_f32 v97, v97, v68, v69
	v_max3_f32 v97, v97, v76, v77
	v_max3_f32 v97, v97, v66, v67
	v_max3_f32 v97, v97, v80, v81
	v_mov_b32_e32 v98, v97
	s_nop 1
	v_permlane32_swap_b32_e32 v97, v98
	v_max_f32_e32 v98, v98, v98
	v_max_f32_e32 v97, v97, v97
	v_max_f32_e32 v97, v97, v98
	v_sub_f32_e32 v98, v97, v227
	v_cmp_ge_f32_e32 vcc, 2.0, v98
	s_cmp_eq_u64 vcc, exec
	v_max_f32_e32 v98, v227, v227
	v_max_f32_e32 v97, v98, v97
	s_cselect_b64 vcc, -1, 0
	v_sub_f32_e32 v98, v227, v97
	v_cndmask_b32_e32 v227, v97, v227, vcc
	v_sub_f32_e32 v82, v82, v227
	v_sub_f32_e32 v72, v72, v227
	v_exp_f32_e32 v82, v82
	v_exp_f32_e32 v72, v72
	v_sub_f32_e32 v83, v83, v227
	v_sub_f32_e32 v73, v73, v227
	v_exp_f32_e32 v83, v83
	v_exp_f32_e32 v73, v73
	v_sub_f32_e32 v84, v84, v227
	v_sub_f32_e32 v78, v78, v227
	v_exp_f32_e32 v84, v84
	v_exp_f32_e32 v78, v78
	v_sub_f32_e32 v85, v85, v227
	v_sub_f32_e32 v75, v75, v227
	v_exp_f32_e32 v85, v85
	v_exp_f32_e32 v75, v75
	v_sub_f32_e32 v86, v86, v227
	v_sub_f32_e32 v70, v70, v227
	v_exp_f32_e32 v97, v98
	v_add_f32_e32 v98, v72, v82
	v_exp_f32_e32 v86, v86
	v_exp_f32_e32 v70, v70
	v_sub_f32_e32 v87, v87, v227
	v_sub_f32_e32 v71, v71, v227
	v_add_f32_e32 v98, 0, v98
	v_add_f32_e32 v99, v73, v83
	v_exp_f32_e32 v87, v87
	v_exp_f32_e32 v71, v71
	v_sub_f32_e32 v88, v88, v227
	v_sub_f32_e32 v74, v74, v227
	v_add_f32_e32 v98, v99, v98
	v_add_f32_e32 v99, v78, v84
	v_exp_f32_e32 v88, v88
	v_exp_f32_e32 v74, v74
	v_sub_f32_e32 v89, v89, v227
	v_sub_f32_e32 v0, v0, v227
	v_add_f32_e32 v98, v99, v98
	v_add_f32_e32 v99, v75, v85
	v_exp_f32_e32 v89, v89
	v_exp_f32_e32 v100, v0
	v_sub_f32_e32 v90, v90, v227
	v_sub_f32_e32 v68, v68, v227
	v_add_f32_e32 v98, v99, v98
	v_add_f32_e32 v99, v70, v86
	v_exp_f32_e32 v90, v90
	v_exp_f32_e32 v68, v68
	v_sub_f32_e32 v91, v91, v227
	v_sub_f32_e32 v69, v69, v227
	v_add_f32_e32 v98, v99, v98
	v_add_f32_e32 v99, v71, v87
	v_exp_f32_e32 v91, v91
	v_exp_f32_e32 v69, v69
	v_sub_f32_e32 v92, v92, v227
	v_sub_f32_e32 v76, v76, v227
	v_add_f32_e32 v0, v99, v98
	v_add_f32_e32 v98, v74, v88
	v_exp_f32_e32 v92, v92
	v_exp_f32_e32 v76, v76
	v_sub_f32_e32 v93, v93, v227
	v_sub_f32_e32 v77, v77, v227
	v_add_f32_e32 v0, v98, v0
	v_add_f32_e32 v98, v100, v89
	v_exp_f32_e32 v93, v93
	v_exp_f32_e32 v77, v77
	v_sub_f32_e32 v94, v94, v227
	v_sub_f32_e32 v66, v66, v227
	v_add_f32_e32 v0, v98, v0
	v_add_f32_e32 v98, v68, v90
	v_exp_f32_e32 v94, v94
	v_exp_f32_e32 v66, v66
	v_sub_f32_e32 v95, v95, v227
	v_sub_f32_e32 v67, v67, v227
	v_add_f32_e32 v0, v98, v0
	v_add_f32_e32 v98, v69, v91
	v_exp_f32_e32 v95, v95
	v_exp_f32_e32 v67, v67
	v_sub_f32_e32 v96, v96, v227
	v_sub_f32_e32 v80, v80, v227
	v_add_f32_e32 v0, v98, v0
	v_add_f32_e32 v98, v76, v92
	v_exp_f32_e32 v96, v96
	v_exp_f32_e32 v80, v80
	v_sub_f32_e32 v79, v79, v227
	v_sub_f32_e32 v81, v81, v227
	v_add_f32_e32 v0, v98, v0
	v_add_f32_e32 v98, v77, v93
	v_exp_f32_e32 v79, v79
	v_exp_f32_e32 v81, v81
	v_add_f32_e32 v0, v98, v0
	v_add_f32_e32 v98, v66, v94
	v_add_f32_e32 v0, v98, v0
	v_add_f32_e32 v98, v67, v95
	v_add_f32_e32 v0, v98, v0
	v_add_f32_e32 v98, v80, v96
	v_add_f32_e32 v0, v98, v0
	v_add_f32_e32 v98, v81, v79
	v_add_f32_e32 v228, v98, v0
	v_cndmask_b32_e64 v0, v97, 1.0, vcc
	v_mov_b32_e32 v229, v228
	v_cvt_pk_bf16_f32 v162, v82, v83
	v_cvt_pk_bf16_f32 v163, v84, v85
	v_cvt_pk_bf16_f32 v164, v86, v87
	v_cvt_pk_bf16_f32 v165, v88, v89
	v_cvt_pk_bf16_f32 v166, v90, v91
	v_cvt_pk_bf16_f32 v167, v92, v93
	v_cvt_pk_bf16_f32 v168, v94, v95
	v_cvt_pk_bf16_f32 v169, v96, v79
	v_cvt_pk_bf16_f32 v170, v72, v73
	v_cvt_pk_bf16_f32 v171, v78, v75
	v_cvt_pk_bf16_f32 v172, v70, v71
	v_cvt_pk_bf16_f32 v173, v74, v100
	v_cvt_pk_bf16_f32 v174, v68, v69
	v_cvt_pk_bf16_f32 v175, v76, v77
	v_cvt_pk_bf16_f32 v176, v66, v67
	v_cvt_pk_bf16_f32 v177, v80, v81
	s_nop 1
	v_permlane32_swap_b32_e32 v228, v229
	v_permlane32_swap_b32_e32 v162, v164
	v_permlane32_swap_b32_e32 v163, v165
	v_permlane32_swap_b32_e32 v166, v168
	v_permlane32_swap_b32_e32 v167, v169
	v_permlane32_swap_b32_e32 v170, v172
	v_permlane32_swap_b32_e32 v171, v173
	v_permlane32_swap_b32_e32 v174, v176
	v_permlane32_swap_b32_e32 v175, v177
	v_cmp_gt_f32_e32 vcc, 1.0, v0
	s_cbranch_vccz .LBB0_857
	s_and_saveexec_b64 s[4:5], s[0:1]
	ds_write_b32 v209, v0
	s_or_b64 exec, exec, s[4:5]
	s_waitcnt lgkmcnt(0)
	ds_read_b128 v[66:69], v192 offset:96
	ds_read_b128 v[70:73], v192 offset:64
	ds_read_b128 v[74:77], v192 offset:32
	ds_read_b128 v[78:81], v192
	s_waitcnt lgkmcnt(0)
	v_pk_mul_f32 v[64:65], v[64:65], v[68:69]
	v_pk_mul_f32 v[60:61], v[60:61], v[72:73]
	v_pk_mul_f32 v[56:57], v[56:57], v[76:77]
	v_pk_mul_f32 v[52:53], v[52:53], v[80:81]
	v_pk_mul_f32 v[62:63], v[62:63], v[66:67]
	v_pk_mul_f32 v[58:59], v[58:59], v[70:71]
	v_pk_mul_f32 v[54:55], v[54:55], v[74:75]
	v_pk_mul_f32 v[50:51], v[50:51], v[78:79]
	v_pk_mul_f32 v[48:49], v[48:49], v[68:69]
	v_pk_mul_f32 v[44:45], v[44:45], v[72:73]
	v_pk_mul_f32 v[40:41], v[40:41], v[76:77]
	v_pk_mul_f32 v[36:37], v[36:37], v[80:81]
	v_pk_mul_f32 v[46:47], v[46:47], v[66:67]
	v_pk_mul_f32 v[42:43], v[42:43], v[70:71]
	v_pk_mul_f32 v[38:39], v[38:39], v[74:75]
	v_pk_mul_f32 v[34:35], v[34:35], v[78:79]
	v_pk_mul_f32 v[32:33], v[32:33], v[68:69]
	v_pk_mul_f32 v[28:29], v[28:29], v[72:73]
	v_pk_mul_f32 v[24:25], v[24:25], v[76:77]
	v_pk_mul_f32 v[20:21], v[20:21], v[80:81]
	v_pk_mul_f32 v[30:31], v[30:31], v[66:67]
	v_pk_mul_f32 v[26:27], v[26:27], v[70:71]
	v_pk_mul_f32 v[22:23], v[22:23], v[74:75]
	v_pk_mul_f32 v[18:19], v[18:19], v[78:79]
	v_pk_mul_f32 v[16:17], v[16:17], v[68:69]
	v_pk_mul_f32 v[12:13], v[12:13], v[72:73]
	v_pk_mul_f32 v[8:9], v[8:9], v[76:77]
	v_pk_mul_f32 v[4:5], v[4:5], v[80:81]
	v_pk_mul_f32 v[14:15], v[14:15], v[66:67]
	v_pk_mul_f32 v[10:11], v[10:11], v[70:71]
	v_pk_mul_f32 v[6:7], v[6:7], v[74:75]
	v_pk_mul_f32 v[2:3], v[2:3], v[78:79]
